# v069 + next tile's K fragments (7 of 8) fetched into free registers during the PV/exp block, so QK starts right after the barrier
# baseline (speedup 1.0000x reference)
; template <int N> __device__ __forceinline__ void wait_bar() { asm volatile("s_waitcnt vmcnt(%0) lgkmcnt(0)\n\ts_barrier" :: "n"(N) : "memory"); }
; #define AT_DMA(tr) do { const unsigned sb_ = (unsigned)__builtin_amdgcn_readfirstlane(dk + (((tr) & (NSTG - 1)) * STAGE)); const size_t ko_ = (size_t)(tr) * 26 * 4096, vo_ = (size_t)(tr) * 640 * 64; \
;         glds16(kg + ko_, sb_ + OFF_K0); if (!WIN) glds16(kg + ko_ + 4096, sb_ + OFF_K1); glds16(vg + vo_, sb_ + OFF_V); if (!WIN) glds16(vg + vo_ + 64 * 64, sb_ + OFF_V + 8192); } while (0)
; template <bool WIN> ...
;     ...
;     for (int tr = 0; tr < NT; ++tr) {
;         if (tr + 2 < NT) wait_bar<2 * NPW>(); else if (tr + 1 < NT) wait_bar<NPW>(); else wait_bar<0>();
;         if (tr + 3 < NT) AT_DMA(tr + 3);
.LSPp_top:
	s_cmpk_gt_u32 s86, 125
	s_cbranch_scc1 .LSPp_t0
	s_waitcnt vmcnt(4) lgkmcnt(0)
	s_barrier

; #define ALAS __attribute__((address_space(3)))
; template <bool WIN> ...
;     ...
;             f32x16 s0, s1;
;             const ALAS unsigned char* sb = lds + (tr & (NSTG - 1)) * STAGE;
;             {
;                 bf16x8 ka[8];
; #pragma unroll
;                 for (int ds = 0; ds < 4; ++ds) { ka[2 * ds] = *(const ALAS bf16x8*)(sb + kx[ds]); ka[2 * ds + 1] = *(const ALAS bf16x8*)(sb + kx[ds] + 4096); }
;                 __builtin_amdgcn_sched_barrier(0);
;                 s0 = __builtin_amdgcn_mfma_f32_32x32x16_bf16(ka[0], qf(0), cvec, 0, 0, 0);
;                 s1 = __builtin_amdgcn_mfma_f32_32x32x16_bf16(ka[1], qf(0), cvec, 0, 0, 0);
; #pragma unroll
;                 for (int ds = 1; ds < 4; ++ds) {
;                     s0 = __builtin_amdgcn_mfma_f32_32x32x16_bf16(ka[2 * ds], qf(ds), s0, 0, 0, 0);
;                     s1 = __builtin_amdgcn_mfma_f32_32x32x16_bf16(ka[2 * ds + 1], qf(ds), s1, 0, 0, 0);
;                 }
;             }
;             bf16x8 va[2 * NDB], vc[2 * NDB];
; #pragma unroll
;             for (int kk = 0; kk < 2; ++kk)
; #pragma unroll
;                 for (int db = 0; db < NDB; ++db) va[kk * NDB + db] = *(const ALAS bf16x8*)(sb + vx[kk] + db * 4096);
;             __builtin_amdgcn_sched_barrier(0);
;             if (near) {
;                 const ALAS float* lb = lut + (k0 + 8 * hi - qabs + LUTC);
; #pragma unroll
;                 for (int r = 0; r < 16; ++r) { s0[r] += lb[16 * (r >> 3) + (r & 7)]; s1[r] += lb[32 + 16 * (r >> 3) + (r & 7)];
;                     if ((r & 7) == 7) __builtin_amdgcn_sched_barrier(0); }
;             }
.LSPp_qk:
	s_add_i32 s87, s85, 0xffff0000
	s_and_b32 s87, s87, 0x18000
	s_add_i32 s99, s85, 0xfffe8000
	s_and_b32 s99, s99, 0x18000
	s_cmp_lg_u32 s86, 0
	s_cbranch_scc1 .LSPp_khave
	v_add3_u32 v203, s87, v178, v162
	ds_read_b128 v[204:207], v203
	ds_read_b128 v[208:211], v203 offset:4096
	v_add3_u32 v203, s87, v180, v162
	ds_read_b128 v[212:215], v203
	ds_read_b128 v[216:219], v203 offset:4096
	v_add3_u32 v203, s87, v182, v162
	ds_read_b128 v[220:223], v203
	ds_read_b128 v[224:227], v203 offset:4096
	v_add3_u32 v203, s87, v184, v162
	ds_read_b128 v[234:237], v203
	ds_read_b128 v[130:133], v203 offset:4096
	s_waitcnt lgkmcnt(0)
	s_branch .LSPp_kgo
.LSPp_khave:
	v_add3_u32 v203, s87, v184, v162
	ds_read_b128 v[130:133], v203 offset:4096
.LSPp_kgo:
	v_mfma_f32_32x32x16_bf16 v[98:113], v[204:207], v[126:129], v[66:81]
	v_mfma_f32_32x32x16_bf16 v[82:97], v[208:211], v[126:129], v[66:81]
	v_mfma_f32_32x32x16_bf16 v[98:113], v[212:215], v[122:125], v[98:113]
	v_mfma_f32_32x32x16_bf16 v[82:97], v[216:219], v[122:125], v[82:97]
	v_mfma_f32_32x32x16_bf16 v[98:113], v[220:223], v[118:121], v[98:113]
	v_mfma_f32_32x32x16_bf16 v[82:97], v[224:227], v[118:121], v[82:97]
	v_mfma_f32_32x32x16_bf16 v[98:113], v[234:237], v[114:117], v[98:113]
	s_waitcnt lgkmcnt(0)
	v_mfma_f32_32x32x16_bf16 v[82:97], v[130:133], v[114:117], v[82:97]
	v_add3_u32 v203, s99, v179, v187
	ds_read_b128 v[146:149], v203 offset:16384
	ds_read_b128 v[150:153], v203 offset:20480
	ds_read_b128 v[154:157], v203 offset:24576
	ds_read_b128 v[158:161], v203 offset:28672
	v_add3_u32 v203, s99, v181, v187
	ds_read_b128 v[130:133], v203 offset:16384
	ds_read_b128 v[134:137], v203 offset:20480
	ds_read_b128 v[138:141], v203 offset:24576
	ds_read_b128 v[142:145], v203 offset:28672
	s_nop 1
	s_andn2_b64 vcc, exec, s[64:65]
	s_cbranch_vccnz .LSPp_pv
	v_add_u32_e32 v203, s84, v171
	v_add_u32_e32 v204, 0x23b80, v203
	v_add_u32_e32 v206, 0x23c00, v203
	v_add_u32_e32 v210, 0x23c08, v203
	v_add_u32_e32 v208, 0x23b88, v203
	v_add_u32_e32 v218, 0x23c10, v203
	v_add_u32_e32 v212, 0x23b90, v203
	v_add_u32_e32 v216, 0x23c18, v203
	v_add_u32_e32 v214, 0x23b98, v203
	ds_read2_b32 v[204:205], v204 offset1:1
	ds_read2_b32 v[206:207], v206 offset1:1
	ds_read2_b32 v[208:209], v208 offset1:1
	ds_read2_b32 v[210:211], v210 offset1:1
	ds_read2_b32 v[212:213], v212 offset1:1
	ds_read2_b32 v[214:215], v214 offset1:1
	ds_read2_b32 v[216:217], v216 offset1:1
	ds_read2_b32 v[218:219], v218 offset1:1
	v_add_u32_e32 v220, 0x23bc0, v203
	v_add_u32_e32 v222, 0x23c40, v203
	v_add_u32_e32 v226, 0x23c48, v203
	v_add_u32_e32 v224, 0x23bc8, v203
	v_add_u32_e32 v228, 0x23bd0, v203
	v_add_u32_e32 v234, 0x23c58, v203
	ds_read2_b32 v[220:221], v220 offset1:1
	ds_read2_b32 v[222:223], v222 offset1:1
	ds_read2_b32 v[224:225], v224 offset1:1
	ds_read2_b32 v[226:227], v226 offset1:1
	v_add_u32_e32 v231, 0x23c50, v203
	v_add_u32_e32 v203, 0x23bd8, v203
	ds_read2_b32 v[228:229], v228 offset1:1
	ds_read2_b32 v[232:233], v203 offset1:1
	ds_read2_b32 v[234:235], v234 offset1:1
	ds_read2_b32 v[236:237], v231 offset1:1
	s_waitcnt lgkmcnt(10)
	v_pk_add_f32 v[104:105], v[104:105], v[214:215]
	v_pk_add_f32 v[102:103], v[102:103], v[212:213]
	v_pk_add_f32 v[100:101], v[100:101], v[208:209]
	s_waitcnt lgkmcnt(2)
	v_pk_add_f32 v[112:113], v[112:113], v[232:233]
	v_pk_add_f32 v[110:111], v[110:111], v[228:229]
	v_pk_add_f32 v[108:109], v[108:109], v[224:225]
	v_pk_add_f32 v[106:107], v[106:107], v[220:221]
	v_pk_add_f32 v[98:99], v[98:99], v[204:205]
	v_pk_add_f32 v[88:89], v[88:89], v[216:217]
	v_pk_add_f32 v[86:87], v[86:87], v[218:219]
	v_pk_add_f32 v[84:85], v[84:85], v[210:211]
	s_waitcnt lgkmcnt(1)
	v_pk_add_f32 v[96:97], v[96:97], v[234:235]
	s_waitcnt lgkmcnt(0)
	v_pk_add_f32 v[94:95], v[94:95], v[236:237]
	v_pk_add_f32 v[92:93], v[92:93], v[226:227]
	v_pk_add_f32 v[90:91], v[90:91], v[222:223]
	v_pk_add_f32 v[82:83], v[82:83], v[206:207]
.LSPp_pv:
	s_cmp_eq_u32 s86, 0
	s_cbranch_scc1 .LSPp_pure
	s_waitcnt lgkmcnt(4)
	v_mfma_f32_32x32x16_bf16 v[50:65], v[146:149], v[238:241], v[50:65]
	v_exp_f32_e32 v98, v98
	v_exp_f32_e32 v99, v99
	v_mfma_f32_32x32x16_bf16 v[34:49], v[150:153], v[238:241], v[34:49]
	v_exp_f32_e32 v100, v100
	v_exp_f32_e32 v101, v101
	v_mfma_f32_32x32x16_bf16 v[18:33], v[154:157], v[238:241], v[18:33]
	v_exp_f32_e32 v102, v102
	v_exp_f32_e32 v103, v103
	v_add_f32_e32 v228, v98, v100
	v_add_f32_e32 v229, v99, v101
	v_mfma_f32_32x32x16_bf16 v[2:17], v[158:161], v[238:241], v[2:17]
	v_exp_f32_e32 v104, v104
	v_exp_f32_e32 v105, v105
	v_add_f32_e32 v228, v228, v102
	v_add_f32_e32 v229, v229, v103
	v_add3_u32 v203, s99, v183, v187
	ds_read_b128 v[146:149], v203 offset:16384
	ds_read_b128 v[150:153], v203 offset:20480
	ds_read_b128 v[154:157], v203 offset:24576
	ds_read_b128 v[158:161], v203 offset:28672
	s_waitcnt lgkmcnt(4)
	v_mfma_f32_32x32x16_bf16 v[50:65], v[130:133], v[242:245], v[50:65]
	v_exp_f32_e32 v106, v106
	v_exp_f32_e32 v107, v107
	v_add_f32_e32 v228, v228, v104
	v_add_f32_e32 v229, v229, v105
	v_cvt_pk_bf16_f32 v238, v98, v99
	v_mfma_f32_32x32x16_bf16 v[34:49], v[134:137], v[242:245], v[34:49]
	v_exp_f32_e32 v108, v108
	v_exp_f32_e32 v109, v109
	v_add_f32_e32 v228, v228, v106
	v_add_f32_e32 v229, v229, v107
	v_cvt_pk_bf16_f32 v239, v100, v101
	v_mfma_f32_32x32x16_bf16 v[18:33], v[138:141], v[242:245], v[18:33]
	v_exp_f32_e32 v110, v110
	v_exp_f32_e32 v111, v111
	v_add_f32_e32 v228, v228, v108
	v_add_f32_e32 v229, v229, v109
	v_cvt_pk_bf16_f32 v240, v102, v103
	v_mfma_f32_32x32x16_bf16 v[2:17], v[142:145], v[242:245], v[2:17]
	v_exp_f32_e32 v112, v112
	v_exp_f32_e32 v113, v113
	v_add_f32_e32 v228, v228, v110
	v_add_f32_e32 v229, v229, v111
	v_cvt_pk_bf16_f32 v241, v104, v105
	v_add3_u32 v203, s99, v190, v187
	ds_read_b128 v[130:133], v203 offset:16384
	ds_read_b128 v[134:137], v203 offset:20480
	ds_read_b128 v[138:141], v203 offset:24576
	ds_read_b128 v[142:145], v203 offset:28672
	s_waitcnt lgkmcnt(4)
; #define ALAS __attribute__((address_space(3)))
; template <bool WIN> ...
;     ...
;             float ls0 = 0.f, ls1 = 0.f;
;     ...
;             union PFU { u32x4 u; bf16x8 b; };
;             PFU p0, p1, p2, p3;
;             AT_EXP(s0, 0, p0);
; #pragma unroll
;             for (int kk = 0; kk < 2; ++kk)
; #pragma unroll
;                 for (int db = 0; db < NDB; ++db) vc[kk * NDB + db] = *(const ALAS bf16x8*)(sb + vx[kk + 2] + db * 4096);
;             __builtin_amdgcn_sched_barrier(0);
; #pragma unroll
;             for (int db = 0; db < NDB; ++db) o[db] = __builtin_amdgcn_mfma_f32_32x32x16_bf16(va[db], p0.b, o[db], 0, 0, 0);
;             AT_EXP(s0, 8, p1);
;             __builtin_amdgcn_sched_barrier(0);
; #pragma unroll
;             for (int db = 0; db < NDB; ++db) o[db] = __builtin_amdgcn_mfma_f32_32x32x16_bf16(va[NDB + db], p1.b, o[db], 0, 0, 0);
;             AT_EXP(s1, 0, p2);
;             __builtin_amdgcn_sched_barrier(0);
; #pragma unroll
;             for (int db = 0; db < NDB; ++db) o[db] = __builtin_amdgcn_mfma_f32_32x32x16_bf16(vc[db], p2.b, o[db], 0, 0, 0);
;             AT_EXP(s1, 8, p3);
;             __builtin_amdgcn_sched_barrier(0);
; #pragma unroll
;             for (int db = 0; db < NDB; ++db) o[db] = __builtin_amdgcn_mfma_f32_32x32x16_bf16(vc[NDB + db], p3.b, o[db], 0, 0, 0);
;             __builtin_amdgcn_sched_barrier(0);
;     ...
;             l_run += ls0 + ls1;
	s_add_i32 s98, s87, 0x8000
	s_and_b32 s98, s98, 0x18000
	v_add3_u32 v203, s98, v178, v162
	ds_read_b128 v[204:207], v203
	ds_read_b128 v[208:211], v203 offset:4096
	v_add3_u32 v203, s98, v180, v162
	ds_read_b128 v[212:215], v203
	ds_read_b128 v[216:219], v203 offset:4096
	v_add3_u32 v203, s98, v182, v162
	ds_read_b128 v[220:223], v203
	ds_read_b128 v[224:227], v203 offset:4096
	v_add3_u32 v203, s98, v184, v162
	ds_read_b128 v[234:237], v203
	v_mfma_f32_32x32x16_bf16 v[50:65], v[146:149], v[246:249], v[50:65]
	v_exp_f32_e32 v82, v82
	v_exp_f32_e32 v83, v83
	v_add_f32_e32 v228, v228, v112
	v_add_f32_e32 v229, v229, v113
	v_cvt_pk_bf16_f32 v242, v106, v107
	v_mfma_f32_32x32x16_bf16 v[34:49], v[150:153], v[246:249], v[34:49]
	v_exp_f32_e32 v84, v84
	v_exp_f32_e32 v85, v85
	v_add_f32_e32 v228, v228, v82
	v_add_f32_e32 v229, v229, v83
	v_cvt_pk_bf16_f32 v243, v108, v109
	v_mfma_f32_32x32x16_bf16 v[18:33], v[154:157], v[246:249], v[18:33]
	v_exp_f32_e32 v86, v86
	v_exp_f32_e32 v87, v87
	v_add_f32_e32 v228, v228, v84
	v_add_f32_e32 v229, v229, v85
	v_cvt_pk_bf16_f32 v244, v110, v111
	v_mfma_f32_32x32x16_bf16 v[2:17], v[158:161], v[246:249], v[2:17]
	v_exp_f32_e32 v88, v88
	v_exp_f32_e32 v89, v89
	v_add_f32_e32 v228, v228, v86
	v_add_f32_e32 v229, v229, v87
	v_cvt_pk_bf16_f32 v245, v112, v113
	s_waitcnt lgkmcnt(7)
	v_mfma_f32_32x32x16_bf16 v[50:65], v[130:133], v[250:253], v[50:65]
	v_exp_f32_e32 v90, v90
	v_exp_f32_e32 v91, v91
	v_add_f32_e32 v228, v228, v88
	v_add_f32_e32 v229, v229, v89
	v_cvt_pk_bf16_f32 v246, v82, v83
	v_mfma_f32_32x32x16_bf16 v[34:49], v[134:137], v[250:253], v[34:49]
	v_exp_f32_e32 v92, v92
	v_exp_f32_e32 v93, v93
	v_add_f32_e32 v228, v228, v90
	v_add_f32_e32 v229, v229, v91
	v_cvt_pk_bf16_f32 v247, v84, v85
	v_mfma_f32_32x32x16_bf16 v[18:33], v[138:141], v[250:253], v[18:33]
	v_exp_f32_e32 v94, v94
	v_exp_f32_e32 v95, v95
	v_add_f32_e32 v228, v228, v92
	v_add_f32_e32 v229, v229, v93
	v_cvt_pk_bf16_f32 v248, v86, v87
	v_mfma_f32_32x32x16_bf16 v[2:17], v[142:145], v[250:253], v[2:17]
	v_exp_f32_e32 v96, v96
	v_exp_f32_e32 v97, v97
	v_add_f32_e32 v228, v228, v94
	v_add_f32_e32 v229, v229, v95
	v_cvt_pk_bf16_f32 v249, v88, v89
	v_add_f32_e32 v228, v228, v96
	v_add_f32_e32 v229, v229, v97
	v_cvt_pk_bf16_f32 v250, v90, v91
	v_cvt_pk_bf16_f32 v251, v92, v93
	v_cvt_pk_bf16_f32 v252, v94, v95
	v_cvt_pk_bf16_f32 v253, v96, v97
	v_add_f32_e32 v228, v228, v229
	v_cmp_nge_f32_e32 vcc, 0x53800000, v228
	s_cbranch_vccnz .LSPp_redo
	s_add_i32 s86, s86, 1
	s_add_i32 s85, s85, 0x8000
	s_addk_i32 s84, 0x100
	s_add_i32 s83, s83, 64
	s_sub_i32 s82, s82, 64
	v_add_f32_e32 v0, v0, v228
	v_lshl_add_u64 v[172:173], v[172:173], 0, s[48:49]
	s_cmpk_eq_u32 s84, 0x8000
	v_lshl_add_u64 v[174:175], v[174:175], 0, s[60:61]
	s_cbranch_scc0 .LSPp_top
	s_branch .LSPp_exit
.LSPp_pure:
	s_waitcnt lgkmcnt(0)
	s_add_i32 s98, s87, 0x8000
	s_and_b32 s98, s98, 0x18000
	v_add3_u32 v203, s98, v178, v162
	ds_read_b128 v[204:207], v203
	ds_read_b128 v[208:211], v203 offset:4096
	v_add3_u32 v203, s98, v180, v162
	ds_read_b128 v[212:215], v203
	ds_read_b128 v[216:219], v203 offset:4096
	v_add3_u32 v203, s98, v182, v162
	ds_read_b128 v[220:223], v203
	ds_read_b128 v[224:227], v203 offset:4096
	v_add3_u32 v203, s98, v184, v162
	ds_read_b128 v[234:237], v203
	v_exp_f32_e32 v98, v98
	v_exp_f32_e32 v99, v99
	v_exp_f32_e32 v100, v100
	v_exp_f32_e32 v101, v101
	v_exp_f32_e32 v102, v102
	v_exp_f32_e32 v103, v103
	v_exp_f32_e32 v104, v104
	v_exp_f32_e32 v105, v105
	v_cvt_pk_bf16_f32 v238, v98, v99
	v_cvt_pk_bf16_f32 v239, v100, v101
	v_cvt_pk_bf16_f32 v240, v102, v103
	v_cvt_pk_bf16_f32 v241, v104, v105
	v_mov_b32_e32 v228, v98
	v_mov_b32_e32 v229, v102
	v_add_f32_e32 v228, v228, v99
	v_add_f32_e32 v229, v229, v103
	v_add_f32_e32 v228, v228, v100
	v_add_f32_e32 v229, v229, v104
	v_add_f32_e32 v228, v228, v101
	v_add_f32_e32 v229, v229, v105
	v_exp_f32_e32 v106, v106
	v_exp_f32_e32 v107, v107
	v_exp_f32_e32 v108, v108
	v_exp_f32_e32 v109, v109
	v_exp_f32_e32 v110, v110
	v_exp_f32_e32 v111, v111
	v_exp_f32_e32 v112, v112
	v_exp_f32_e32 v113, v113
	v_cvt_pk_bf16_f32 v242, v106, v107
	v_cvt_pk_bf16_f32 v243, v108, v109
	v_cvt_pk_bf16_f32 v244, v110, v111
	v_cvt_pk_bf16_f32 v245, v112, v113
	v_add_f32_e32 v228, v228, v106
	v_add_f32_e32 v229, v229, v110
	v_add_f32_e32 v228, v228, v107
	v_add_f32_e32 v229, v229, v111
	v_add_f32_e32 v228, v228, v108
	v_add_f32_e32 v229, v229, v112
	v_add_f32_e32 v228, v228, v109
	v_add_f32_e32 v229, v229, v113
	v_exp_f32_e32 v82, v82
	v_exp_f32_e32 v83, v83
	v_exp_f32_e32 v84, v84
	v_exp_f32_e32 v85, v85
	v_exp_f32_e32 v86, v86
	v_exp_f32_e32 v87, v87
	v_exp_f32_e32 v88, v88
	v_exp_f32_e32 v89, v89
	v_cvt_pk_bf16_f32 v246, v82, v83
	v_cvt_pk_bf16_f32 v247, v84, v85
	v_cvt_pk_bf16_f32 v248, v86, v87
	v_cvt_pk_bf16_f32 v249, v88, v89
	v_add_f32_e32 v228, v228, v82
	v_add_f32_e32 v229, v229, v86
	v_add_f32_e32 v228, v228, v83
	v_add_f32_e32 v229, v229, v87
	v_add_f32_e32 v228, v228, v84
	v_add_f32_e32 v229, v229, v88
	v_add_f32_e32 v228, v228, v85
	v_add_f32_e32 v229, v229, v89
	v_exp_f32_e32 v90, v90
	v_exp_f32_e32 v91, v91
	v_exp_f32_e32 v92, v92
	v_exp_f32_e32 v93, v93
	v_exp_f32_e32 v94, v94
	v_exp_f32_e32 v95, v95
	v_exp_f32_e32 v96, v96
	v_exp_f32_e32 v97, v97
	v_cvt_pk_bf16_f32 v250, v90, v91
	v_cvt_pk_bf16_f32 v251, v92, v93
	v_cvt_pk_bf16_f32 v252, v94, v95
	v_cvt_pk_bf16_f32 v253, v96, v97
	v_add_f32_e32 v228, v228, v90
	v_add_f32_e32 v229, v229, v94
	v_add_f32_e32 v228, v228, v91
	v_add_f32_e32 v229, v229, v95
	v_add_f32_e32 v228, v228, v92
	v_add_f32_e32 v229, v229, v96
	v_add_f32_e32 v228, v228, v93
	v_add_f32_e32 v229, v229, v97
	v_add_f32_e32 v228, v228, v229
	v_cmp_nge_f32_e32 vcc, 0x53800000, v228
	s_cbranch_vccnz .LSPp_redo
	s_add_i32 s86, s86, 1
	s_add_i32 s85, s85, 0x8000
	s_addk_i32 s84, 0x100
	s_add_i32 s83, s83, 64
	s_sub_i32 s82, s82, 64
	v_add_f32_e32 v0, v0, v228
	v_lshl_add_u64 v[172:173], v[172:173], 0, s[48:49]
	s_cmpk_eq_u32 s84, 0x8000
	v_lshl_add_u64 v[174:175], v[174:175], 0, s[60:61]
	s_cbranch_scc0 .LSPp_top
	s_branch .LSPp_exit
; #define ALAS __attribute__((address_space(3)))
; template <bool WIN> ...
;     ...
;             f32x16 s0, s1;
;             const ALAS unsigned char* sb = lds + (tr & (NSTG - 1)) * STAGE;
;             {
;                 bf16x8 ka[8];
; #pragma unroll
;                 for (int ds = 0; ds < 4; ++ds) { ka[2 * ds] = *(const ALAS bf16x8*)(sb + kx[ds]); ka[2 * ds + 1] = *(const ALAS bf16x8*)(sb + kx[ds] + 4096); }
;                 __builtin_amdgcn_sched_barrier(0);
;                 s0 = __builtin_amdgcn_mfma_f32_32x32x16_bf16(ka[0], qf(0), cvec, 0, 0, 0);
;                 s1 = __builtin_amdgcn_mfma_f32_32x32x16_bf16(ka[1], qf(0), cvec, 0, 0, 0);
; #pragma unroll
;                 for (int ds = 1; ds < 4; ++ds) {
;                     s0 = __builtin_amdgcn_mfma_f32_32x32x16_bf16(ka[2 * ds], qf(ds), s0, 0, 0, 0);
;                     s1 = __builtin_amdgcn_mfma_f32_32x32x16_bf16(ka[2 * ds + 1], qf(ds), s1, 0, 0, 0);
;                 }
;             }
;             bf16x8 va[2 * NDB], vc[2 * NDB];
; #pragma unroll
;             for (int kk = 0; kk < 2; ++kk)
; #pragma unroll
;                 for (int db = 0; db < NDB; ++db) va[kk * NDB + db] = *(const ALAS bf16x8*)(sb + vx[kk] + db * 4096);
;             __builtin_amdgcn_sched_barrier(0);
;             if (near) {
;                 const ALAS float* lb = lut + (k0 + 8 * hi - qabs + LUTC);
; #pragma unroll
;                 for (int r = 0; r < 16; ++r) { s0[r] += lb[16 * (r >> 3) + (r & 7)]; s1[r] += lb[32 + 16 * (r >> 3) + (r & 7)];
;                     if ((r & 7) == 7) __builtin_amdgcn_sched_barrier(0); }
;             }
.LSPp_redo:
	v_add3_u32 v203, s87, v178, v162
	ds_read_b128 v[204:207], v203
	ds_read_b128 v[208:211], v203 offset:4096
	v_add3_u32 v203, s87, v180, v162
	ds_read_b128 v[212:215], v203
	ds_read_b128 v[216:219], v203 offset:4096
	v_add3_u32 v203, s87, v182, v162
	ds_read_b128 v[220:223], v203
	ds_read_b128 v[224:227], v203 offset:4096
	v_add3_u32 v203, s87, v184, v162
	ds_read_b128 v[234:237], v203
	ds_read_b128 v[130:133], v203 offset:4096
	s_waitcnt lgkmcnt(0)
	v_mfma_f32_32x32x16_bf16 v[98:113], v[204:207], v[126:129], v[66:81]
	v_mfma_f32_32x32x16_bf16 v[82:97], v[208:211], v[126:129], v[66:81]
	v_mfma_f32_32x32x16_bf16 v[98:113], v[212:215], v[122:125], v[98:113]
	v_mfma_f32_32x32x16_bf16 v[82:97], v[216:219], v[122:125], v[82:97]
	v_mfma_f32_32x32x16_bf16 v[98:113], v[220:223], v[118:121], v[98:113]
	v_mfma_f32_32x32x16_bf16 v[82:97], v[224:227], v[118:121], v[82:97]
	v_mfma_f32_32x32x16_bf16 v[98:113], v[234:237], v[114:117], v[98:113]
	v_mfma_f32_32x32x16_bf16 v[82:97], v[130:133], v[114:117], v[82:97]
	s_nop 7
	s_nop 7
	s_andn2_b64 vcc, exec, s[64:65]
	s_cbranch_vccnz .LSPp_redomax
	v_add_u32_e32 v203, s84, v171
	v_add_u32_e32 v204, 0x23b80, v203
	v_add_u32_e32 v206, 0x23c00, v203
	v_add_u32_e32 v210, 0x23c08, v203
	v_add_u32_e32 v208, 0x23b88, v203
	v_add_u32_e32 v218, 0x23c10, v203
	v_add_u32_e32 v212, 0x23b90, v203
	v_add_u32_e32 v216, 0x23c18, v203
	v_add_u32_e32 v214, 0x23b98, v203
	ds_read2_b32 v[204:205], v204 offset1:1
	ds_read2_b32 v[206:207], v206 offset1:1
	ds_read2_b32 v[208:209], v208 offset1:1
	ds_read2_b32 v[210:211], v210 offset1:1
	ds_read2_b32 v[212:213], v212 offset1:1
	ds_read2_b32 v[214:215], v214 offset1:1
	ds_read2_b32 v[216:217], v216 offset1:1
	ds_read2_b32 v[218:219], v218 offset1:1
	v_add_u32_e32 v220, 0x23bc0, v203
	v_add_u32_e32 v222, 0x23c40, v203
	v_add_u32_e32 v226, 0x23c48, v203
	v_add_u32_e32 v224, 0x23bc8, v203
	v_add_u32_e32 v228, 0x23bd0, v203
	v_add_u32_e32 v234, 0x23c58, v203
	ds_read2_b32 v[220:221], v220 offset1:1
	ds_read2_b32 v[222:223], v222 offset1:1
	ds_read2_b32 v[224:225], v224 offset1:1
	ds_read2_b32 v[226:227], v226 offset1:1
	v_add_u32_e32 v231, 0x23c50, v203
	v_add_u32_e32 v203, 0x23bd8, v203
	ds_read2_b32 v[228:229], v228 offset1:1
	ds_read2_b32 v[232:233], v203 offset1:1
	ds_read2_b32 v[234:235], v234 offset1:1
	ds_read2_b32 v[236:237], v231 offset1:1
	s_waitcnt lgkmcnt(10)
	v_pk_add_f32 v[104:105], v[104:105], v[214:215]
	v_pk_add_f32 v[102:103], v[102:103], v[212:213]
	v_pk_add_f32 v[100:101], v[100:101], v[208:209]
	s_waitcnt lgkmcnt(2)
	v_pk_add_f32 v[112:113], v[112:113], v[232:233]
	v_pk_add_f32 v[110:111], v[110:111], v[228:229]
	v_pk_add_f32 v[108:109], v[108:109], v[224:225]
	v_pk_add_f32 v[106:107], v[106:107], v[220:221]
	v_pk_add_f32 v[98:99], v[98:99], v[204:205]
	v_pk_add_f32 v[88:89], v[88:89], v[216:217]
	v_pk_add_f32 v[86:87], v[86:87], v[218:219]
	v_pk_add_f32 v[84:85], v[84:85], v[210:211]
	s_waitcnt lgkmcnt(1)
	v_pk_add_f32 v[96:97], v[96:97], v[234:235]
	s_waitcnt lgkmcnt(0)
	v_pk_add_f32 v[94:95], v[94:95], v[236:237]
	v_pk_add_f32 v[92:93], v[92:93], v[226:227]
	v_pk_add_f32 v[90:91], v[90:91], v[222:223]
	v_pk_add_f32 v[82:83], v[82:83], v[206:207]

; #define ALAS __attribute__((address_space(3)))
; template <bool WIN> ...
;     ...
;             union PFU { u32x4 u; bf16x8 b; };
;             PFU p0, p1, p2, p3;
;             AT_EXP(s0, 0, p0);
; #pragma unroll
;             for (int kk = 0; kk < 2; ++kk)
; #pragma unroll
;                 for (int db = 0; db < NDB; ++db) vc[kk * NDB + db] = *(const ALAS bf16x8*)(sb + vx[kk + 2] + db * 4096);
;             __builtin_amdgcn_sched_barrier(0);
; #pragma unroll
;             for (int db = 0; db < NDB; ++db) o[db] = __builtin_amdgcn_mfma_f32_32x32x16_bf16(va[db], p0.b, o[db], 0, 0, 0);
;             AT_EXP(s0, 8, p1);
;             __builtin_amdgcn_sched_barrier(0);
; #pragma unroll
;             for (int db = 0; db < NDB; ++db) o[db] = __builtin_amdgcn_mfma_f32_32x32x16_bf16(va[NDB + db], p1.b, o[db], 0, 0, 0);
;             AT_EXP(s1, 0, p2);
;             __builtin_amdgcn_sched_barrier(0);
; #pragma unroll
;             for (int db = 0; db < NDB; ++db) o[db] = __builtin_amdgcn_mfma_f32_32x32x16_bf16(vc[db], p2.b, o[db], 0, 0, 0);
;             AT_EXP(s1, 8, p3);
;             __builtin_amdgcn_sched_barrier(0);
; #pragma unroll
;             for (int db = 0; db < NDB; ++db) o[db] = __builtin_amdgcn_mfma_f32_32x32x16_bf16(vc[NDB + db], p3.b, o[db], 0, 0, 0);
;             __builtin_amdgcn_sched_barrier(0);
;     ...
;             l_run += ls0 + ls1;
.LSPp_pure2:
	s_waitcnt lgkmcnt(0)
	s_add_i32 s98, s87, 0x8000
	s_and_b32 s98, s98, 0x18000
	v_add3_u32 v203, s98, v178, v162
	ds_read_b128 v[204:207], v203
	ds_read_b128 v[208:211], v203 offset:4096
	v_add3_u32 v203, s98, v180, v162
	ds_read_b128 v[212:215], v203
	ds_read_b128 v[216:219], v203 offset:4096
	v_add3_u32 v203, s98, v182, v162
	ds_read_b128 v[220:223], v203
	ds_read_b128 v[224:227], v203 offset:4096
	v_add3_u32 v203, s98, v184, v162
	ds_read_b128 v[234:237], v203
	v_exp_f32_e32 v98, v98
	v_exp_f32_e32 v99, v99
	v_exp_f32_e32 v100, v100
	v_exp_f32_e32 v101, v101
	v_exp_f32_e32 v102, v102
	v_exp_f32_e32 v103, v103
	v_exp_f32_e32 v104, v104
	v_exp_f32_e32 v105, v105
	v_cvt_pk_bf16_f32 v238, v98, v99
	v_cvt_pk_bf16_f32 v239, v100, v101
	v_cvt_pk_bf16_f32 v240, v102, v103
	v_cvt_pk_bf16_f32 v241, v104, v105
	v_mov_b32_e32 v228, v98
	v_mov_b32_e32 v229, v102
	v_add_f32_e32 v228, v228, v99
	v_add_f32_e32 v229, v229, v103
	v_add_f32_e32 v228, v228, v100
	v_add_f32_e32 v229, v229, v104
	v_add_f32_e32 v228, v228, v101
	v_add_f32_e32 v229, v229, v105
	v_exp_f32_e32 v106, v106
	v_exp_f32_e32 v107, v107
	v_exp_f32_e32 v108, v108
	v_exp_f32_e32 v109, v109
	v_exp_f32_e32 v110, v110
	v_exp_f32_e32 v111, v111
	v_exp_f32_e32 v112, v112
	v_exp_f32_e32 v113, v113
	v_cvt_pk_bf16_f32 v242, v106, v107
	v_cvt_pk_bf16_f32 v243, v108, v109
	v_cvt_pk_bf16_f32 v244, v110, v111
	v_cvt_pk_bf16_f32 v245, v112, v113
	v_add_f32_e32 v228, v228, v106
	v_add_f32_e32 v229, v229, v110
	v_add_f32_e32 v228, v228, v107
	v_add_f32_e32 v229, v229, v111
	v_add_f32_e32 v228, v228, v108
	v_add_f32_e32 v229, v229, v112
	v_add_f32_e32 v228, v228, v109
	v_add_f32_e32 v229, v229, v113
	v_exp_f32_e32 v82, v82
	v_exp_f32_e32 v83, v83
	v_exp_f32_e32 v84, v84
	v_exp_f32_e32 v85, v85
	v_exp_f32_e32 v86, v86
	v_exp_f32_e32 v87, v87
	v_exp_f32_e32 v88, v88
	v_exp_f32_e32 v89, v89
	v_cvt_pk_bf16_f32 v246, v82, v83
	v_cvt_pk_bf16_f32 v247, v84, v85
	v_cvt_pk_bf16_f32 v248, v86, v87
	v_cvt_pk_bf16_f32 v249, v88, v89
	v_add_f32_e32 v228, v228, v82
	v_add_f32_e32 v229, v229, v86
	v_add_f32_e32 v228, v228, v83
	v_add_f32_e32 v229, v229, v87
	v_add_f32_e32 v228, v228, v84
	v_add_f32_e32 v229, v229, v88
	v_add_f32_e32 v228, v228, v85
	v_add_f32_e32 v229, v229, v89
	v_exp_f32_e32 v90, v90
	v_exp_f32_e32 v91, v91
	v_exp_f32_e32 v92, v92
	v_exp_f32_e32 v93, v93
	v_exp_f32_e32 v94, v94
	v_exp_f32_e32 v95, v95
	v_exp_f32_e32 v96, v96
	v_exp_f32_e32 v97, v97
	v_cvt_pk_bf16_f32 v250, v90, v91
	v_cvt_pk_bf16_f32 v251, v92, v93
	v_cvt_pk_bf16_f32 v252, v94, v95
	v_cvt_pk_bf16_f32 v253, v96, v97
	v_add_f32_e32 v228, v228, v90
	v_add_f32_e32 v229, v229, v94
	v_add_f32_e32 v228, v228, v91
	v_add_f32_e32 v229, v229, v95
	v_add_f32_e32 v228, v228, v92
	v_add_f32_e32 v229, v229, v96
	v_add_f32_e32 v228, v228, v93
	v_add_f32_e32 v229, v229, v97
	v_add_f32_e32 v228, v228, v229
	s_add_i32 s86, s86, 1
	s_add_i32 s85, s85, 0x8000
	s_addk_i32 s84, 0x100
	s_add_i32 s83, s83, 64
	s_sub_i32 s82, s82, 64
	v_add_f32_e32 v0, v0, v228
	v_lshl_add_u64 v[172:173], v[172:173], 0, s[48:49]
	s_cmpk_eq_u32 s84, 0x8000
	v_lshl_add_u64 v[174:175], v[174:175], 0, s[60:61]
	s_cbranch_scc0 .LSPp_top
	s_branch .LSPp_exit
.LSPp_exit:
	s_add_i32 s99, s85, 0xfffe8000
	s_and_b32 s99, s99, 0x18000
	v_add3_u32 v203, s99, v179, v187
	ds_read_b128 v[146:149], v203 offset:16384
	ds_read_b128 v[150:153], v203 offset:20480
	ds_read_b128 v[154:157], v203 offset:24576
	ds_read_b128 v[158:161], v203 offset:28672
	v_add3_u32 v203, s99, v181, v187
	ds_read_b128 v[130:133], v203 offset:16384
	ds_read_b128 v[134:137], v203 offset:20480
	ds_read_b128 v[138:141], v203 offset:24576
	ds_read_b128 v[142:145], v203 offset:28672
	s_waitcnt lgkmcnt(4)
	v_mfma_f32_32x32x16_bf16 v[50:65], v[146:149], v[238:241], v[50:65]
	v_mfma_f32_32x32x16_bf16 v[34:49], v[150:153], v[238:241], v[34:49]
	v_mfma_f32_32x32x16_bf16 v[18:33], v[154:157], v[238:241], v[18:33]
	v_mfma_f32_32x32x16_bf16 v[2:17], v[158:161], v[238:241], v[2:17]
	v_add3_u32 v203, s99, v183, v187
	ds_read_b128 v[146:149], v203 offset:16384
	ds_read_b128 v[150:153], v203 offset:20480
	ds_read_b128 v[154:157], v203 offset:24576
	ds_read_b128 v[158:161], v203 offset:28672
	s_waitcnt lgkmcnt(4)
	v_mfma_f32_32x32x16_bf16 v[50:65], v[130:133], v[242:245], v[50:65]
	v_mfma_f32_32x32x16_bf16 v[34:49], v[134:137], v[242:245], v[34:49]
	v_mfma_f32_32x32x16_bf16 v[18:33], v[138:141], v[242:245], v[18:33]
	v_mfma_f32_32x32x16_bf16 v[2:17], v[142:145], v[242:245], v[2:17]
	v_add3_u32 v203, s99, v190, v187
	ds_read_b128 v[130:133], v203 offset:16384
	ds_read_b128 v[134:137], v203 offset:20480
	ds_read_b128 v[138:141], v203 offset:24576
	ds_read_b128 v[142:145], v203 offset:28672
	s_waitcnt lgkmcnt(4)
	v_mfma_f32_32x32x16_bf16 v[50:65], v[146:149], v[246:249], v[50:65]
	v_mfma_f32_32x32x16_bf16 v[34:49], v[150:153], v[246:249], v[34:49]
	v_mfma_f32_32x32x16_bf16 v[18:33], v[154:157], v[246:249], v[18:33]
	v_mfma_f32_32x32x16_bf16 v[2:17], v[158:161], v[246:249], v[2:17]
	s_waitcnt lgkmcnt(0)
	v_mfma_f32_32x32x16_bf16 v[50:65], v[130:133], v[250:253], v[50:65]
	v_mfma_f32_32x32x16_bf16 v[34:49], v[134:137], v[250:253], v[34:49]
	v_mfma_f32_32x32x16_bf16 v[18:33], v[138:141], v[250:253], v[18:33]
	v_mfma_f32_32x32x16_bf16 v[2:17], v[142:145], v[250:253], v[2:17]
	s_branch .LBB0_262

; template <int N> __device__ __forceinline__ void wait_bar() { asm volatile("s_waitcnt vmcnt(%0) lgkmcnt(0)\n\ts_barrier" :: "n"(N) : "memory"); }
; #define AT_DMA(tr) do { const unsigned sb_ = (unsigned)__builtin_amdgcn_readfirstlane(dk + (((tr) & (NSTG - 1)) * STAGE)); const size_t ko_ = (size_t)(tr) * 26 * 4096, vo_ = (size_t)(tr) * 640 * 64; \
;         glds16(kg + ko_, sb_ + OFF_K0); if (!WIN) glds16(kg + ko_ + 4096, sb_ + OFF_K1); glds16(vg + vo_, sb_ + OFF_V); if (!WIN) glds16(vg + vo_ + 64 * 64, sb_ + OFF_V + 8192); } while (0)
; template <bool WIN> ...
;     ...
;     for (int tr = 0; tr < NT; ++tr) {
;         if (tr + 2 < NT) wait_bar<2 * NPW>(); else if (tr + 1 < NT) wait_bar<NPW>(); else wait_bar<0>();
;         if (tr + 3 < NT) AT_DMA(tr + 3);
.LSPs_top:
	s_cmpk_gt_u32 s79, 29
	s_cbranch_scc1 .LSPs_t0
	s_waitcnt vmcnt(4) lgkmcnt(0)
	s_barrier

; #define ALAS __attribute__((address_space(3)))
; template <bool WIN> ...
;     ...
;             f32x16 s0, s1;
;             const ALAS unsigned char* sb = lds + (tr & (NSTG - 1)) * STAGE;
;             {
;                 bf16x8 ka[8];
; #pragma unroll
;                 for (int ds = 0; ds < 4; ++ds) { ka[2 * ds] = *(const ALAS bf16x8*)(sb + kx[ds]); ka[2 * ds + 1] = *(const ALAS bf16x8*)(sb + kx[ds] + 4096); }
;                 __builtin_amdgcn_sched_barrier(0);
;                 s0 = __builtin_amdgcn_mfma_f32_32x32x16_bf16(ka[0], qf(0), cvec, 0, 0, 0);
;                 s1 = __builtin_amdgcn_mfma_f32_32x32x16_bf16(ka[1], qf(0), cvec, 0, 0, 0);
; #pragma unroll
;                 for (int ds = 1; ds < 4; ++ds) {
;                     s0 = __builtin_amdgcn_mfma_f32_32x32x16_bf16(ka[2 * ds], qf(ds), s0, 0, 0, 0);
;                     s1 = __builtin_amdgcn_mfma_f32_32x32x16_bf16(ka[2 * ds + 1], qf(ds), s1, 0, 0, 0);
;                 }
;             }
;             bf16x8 va[2 * NDB], vc[2 * NDB];
; #pragma unroll
;             for (int kk = 0; kk < 2; ++kk)
; #pragma unroll
;                 for (int db = 0; db < NDB; ++db) va[kk * NDB + db] = *(const ALAS bf16x8*)(sb + vx[kk] + db * 4096);
;             __builtin_amdgcn_sched_barrier(0);
;             if (near) {
;                 const ALAS float* lb = lut + (k0 + 8 * hi - qabs + LUTC);
; #pragma unroll
;                 for (int r = 0; r < 16; ++r) { s0[r] += lb[16 * (r >> 3) + (r & 7)]; s1[r] += lb[32 + 16 * (r >> 3) + (r & 7)];
;                     if ((r & 7) == 7) __builtin_amdgcn_sched_barrier(0); }
;             }
.LSPs_qk:
	s_add_i32 s80, s78, 0xffff0000
	s_and_b32 s80, s80, 0x18000
	s_add_i32 s99, s78, 0xfffe8000
	s_and_b32 s99, s99, 0x18000
	s_cmp_lg_u32 s79, 0
	s_cbranch_scc1 .LSPs_khave
	v_add3_u32 v203, s80, v178, v162
	ds_read_b128 v[204:207], v203
	ds_read_b128 v[208:211], v203 offset:4096
	v_add3_u32 v203, s80, v180, v162
	ds_read_b128 v[212:215], v203
	ds_read_b128 v[216:219], v203 offset:4096
	v_add3_u32 v203, s80, v182, v162
	ds_read_b128 v[220:223], v203
	ds_read_b128 v[224:227], v203 offset:4096
	v_add3_u32 v203, s80, v184, v162
	ds_read_b128 v[234:237], v203
	ds_read_b128 v[130:133], v203 offset:4096
	s_waitcnt lgkmcnt(0)
	s_branch .LSPs_kgo
.LSPs_khave:
	v_add3_u32 v203, s80, v184, v162
	ds_read_b128 v[130:133], v203 offset:4096
.LSPs_kgo:
	v_mfma_f32_32x32x16_bf16 v[98:113], v[204:207], v[126:129], v[66:81]
	v_mfma_f32_32x32x16_bf16 v[82:97], v[208:211], v[126:129], v[66:81]
	v_mfma_f32_32x32x16_bf16 v[98:113], v[212:215], v[122:125], v[98:113]
	v_mfma_f32_32x32x16_bf16 v[82:97], v[216:219], v[122:125], v[82:97]
	v_mfma_f32_32x32x16_bf16 v[98:113], v[220:223], v[118:121], v[98:113]
	v_mfma_f32_32x32x16_bf16 v[82:97], v[224:227], v[118:121], v[82:97]
	v_mfma_f32_32x32x16_bf16 v[98:113], v[234:237], v[114:117], v[98:113]
	s_waitcnt lgkmcnt(0)
	v_mfma_f32_32x32x16_bf16 v[82:97], v[130:133], v[114:117], v[82:97]
	v_add3_u32 v203, s99, v179, v187
	ds_read_b128 v[146:149], v203 offset:16384
	ds_read_b128 v[150:153], v203 offset:20480
	ds_read_b128 v[154:157], v203 offset:24576
	ds_read_b128 v[158:161], v203 offset:28672
	v_add3_u32 v203, s99, v181, v187
	ds_read_b128 v[130:133], v203 offset:16384
	ds_read_b128 v[134:137], v203 offset:20480
	ds_read_b128 v[138:141], v203 offset:24576
	ds_read_b128 v[142:145], v203 offset:28672
	s_nop 1
	s_andn2_b64 vcc, exec, s[64:65]
	s_cbranch_vccnz .LSPs_pv
	v_add_u32_e32 v203, s77, v171
	v_add_u32_e32 v204, 0x23b80, v203
	v_add_u32_e32 v206, 0x23c00, v203
	v_add_u32_e32 v210, 0x23c08, v203
	v_add_u32_e32 v208, 0x23b88, v203
	v_add_u32_e32 v218, 0x23c10, v203
	v_add_u32_e32 v212, 0x23b90, v203
	v_add_u32_e32 v216, 0x23c18, v203
	v_add_u32_e32 v214, 0x23b98, v203
	ds_read2_b32 v[204:205], v204 offset1:1
	ds_read2_b32 v[206:207], v206 offset1:1
	ds_read2_b32 v[208:209], v208 offset1:1
	ds_read2_b32 v[210:211], v210 offset1:1
	ds_read2_b32 v[212:213], v212 offset1:1
	ds_read2_b32 v[214:215], v214 offset1:1
	ds_read2_b32 v[216:217], v216 offset1:1
	ds_read2_b32 v[218:219], v218 offset1:1
	v_add_u32_e32 v220, 0x23bc0, v203
	v_add_u32_e32 v222, 0x23c40, v203
	v_add_u32_e32 v226, 0x23c48, v203
	v_add_u32_e32 v224, 0x23bc8, v203
	v_add_u32_e32 v228, 0x23bd0, v203
	v_add_u32_e32 v234, 0x23c58, v203
	ds_read2_b32 v[220:221], v220 offset1:1
	ds_read2_b32 v[222:223], v222 offset1:1
	ds_read2_b32 v[224:225], v224 offset1:1
	ds_read2_b32 v[226:227], v226 offset1:1
	v_add_u32_e32 v231, 0x23c50, v203
	v_add_u32_e32 v203, 0x23bd8, v203
	ds_read2_b32 v[228:229], v228 offset1:1
	ds_read2_b32 v[232:233], v203 offset1:1
	ds_read2_b32 v[234:235], v234 offset1:1
	ds_read2_b32 v[236:237], v231 offset1:1
	s_waitcnt lgkmcnt(10)
	v_pk_add_f32 v[104:105], v[104:105], v[214:215]
	v_pk_add_f32 v[102:103], v[102:103], v[212:213]
	v_pk_add_f32 v[100:101], v[100:101], v[208:209]
	s_waitcnt lgkmcnt(2)
	v_pk_add_f32 v[112:113], v[112:113], v[232:233]
	v_pk_add_f32 v[110:111], v[110:111], v[228:229]
	v_pk_add_f32 v[108:109], v[108:109], v[224:225]
	v_pk_add_f32 v[106:107], v[106:107], v[220:221]
	v_pk_add_f32 v[98:99], v[98:99], v[204:205]
	v_pk_add_f32 v[88:89], v[88:89], v[216:217]
	v_pk_add_f32 v[86:87], v[86:87], v[218:219]
	v_pk_add_f32 v[84:85], v[84:85], v[210:211]
	s_waitcnt lgkmcnt(1)
	v_pk_add_f32 v[96:97], v[96:97], v[234:235]
	s_waitcnt lgkmcnt(0)
	v_pk_add_f32 v[94:95], v[94:95], v[236:237]
	v_pk_add_f32 v[92:93], v[92:93], v[226:227]
	v_pk_add_f32 v[90:91], v[90:91], v[222:223]
	v_pk_add_f32 v[82:83], v[82:83], v[206:207]
.LSPs_pv:
	s_cmp_eq_u32 s79, 0
	s_cbranch_scc1 .LSPs_pure
	s_waitcnt lgkmcnt(4)
	v_mfma_f32_32x32x16_bf16 v[50:65], v[146:149], v[238:241], v[50:65]
	v_exp_f32_e32 v98, v98
	v_exp_f32_e32 v99, v99
	v_mfma_f32_32x32x16_bf16 v[34:49], v[150:153], v[238:241], v[34:49]
	v_exp_f32_e32 v100, v100
	v_exp_f32_e32 v101, v101
	v_mfma_f32_32x32x16_bf16 v[18:33], v[154:157], v[238:241], v[18:33]
	v_exp_f32_e32 v102, v102
	v_exp_f32_e32 v103, v103
	v_add_f32_e32 v228, v98, v100
	v_add_f32_e32 v229, v99, v101
	v_mfma_f32_32x32x16_bf16 v[2:17], v[158:161], v[238:241], v[2:17]
	v_exp_f32_e32 v104, v104
	v_exp_f32_e32 v105, v105
	v_add_f32_e32 v228, v228, v102
	v_add_f32_e32 v229, v229, v103
	v_add3_u32 v203, s99, v183, v187
	ds_read_b128 v[146:149], v203 offset:16384
	ds_read_b128 v[150:153], v203 offset:20480
	ds_read_b128 v[154:157], v203 offset:24576
	ds_read_b128 v[158:161], v203 offset:28672
	s_waitcnt lgkmcnt(4)
	v_mfma_f32_32x32x16_bf16 v[50:65], v[130:133], v[242:245], v[50:65]
	v_exp_f32_e32 v106, v106
	v_exp_f32_e32 v107, v107
	v_add_f32_e32 v228, v228, v104
	v_add_f32_e32 v229, v229, v105
	v_cvt_pk_bf16_f32 v238, v98, v99
	v_mfma_f32_32x32x16_bf16 v[34:49], v[134:137], v[242:245], v[34:49]
	v_exp_f32_e32 v108, v108
	v_exp_f32_e32 v109, v109
	v_add_f32_e32 v228, v228, v106
	v_add_f32_e32 v229, v229, v107
	v_cvt_pk_bf16_f32 v239, v100, v101
	v_mfma_f32_32x32x16_bf16 v[18:33], v[138:141], v[242:245], v[18:33]
	v_exp_f32_e32 v110, v110
	v_exp_f32_e32 v111, v111
	v_add_f32_e32 v228, v228, v108
	v_add_f32_e32 v229, v229, v109
	v_cvt_pk_bf16_f32 v240, v102, v103
	v_mfma_f32_32x32x16_bf16 v[2:17], v[142:145], v[242:245], v[2:17]
	v_exp_f32_e32 v112, v112
	v_exp_f32_e32 v113, v113
	v_add_f32_e32 v228, v228, v110
	v_add_f32_e32 v229, v229, v111
	v_cvt_pk_bf16_f32 v241, v104, v105
	v_add3_u32 v203, s99, v190, v187
	ds_read_b128 v[130:133], v203 offset:16384
	ds_read_b128 v[134:137], v203 offset:20480
	ds_read_b128 v[138:141], v203 offset:24576
	ds_read_b128 v[142:145], v203 offset:28672
	s_waitcnt lgkmcnt(4)
; #define ALAS __attribute__((address_space(3)))
; template <bool WIN> ...
;     ...
;             float ls0 = 0.f, ls1 = 0.f;
;     ...
;             union PFU { u32x4 u; bf16x8 b; };
;             PFU p0, p1, p2, p3;
;             AT_EXP(s0, 0, p0);
; #pragma unroll
;             for (int kk = 0; kk < 2; ++kk)
; #pragma unroll
;                 for (int db = 0; db < NDB; ++db) vc[kk * NDB + db] = *(const ALAS bf16x8*)(sb + vx[kk + 2] + db * 4096);
;             __builtin_amdgcn_sched_barrier(0);
; #pragma unroll
;             for (int db = 0; db < NDB; ++db) o[db] = __builtin_amdgcn_mfma_f32_32x32x16_bf16(va[db], p0.b, o[db], 0, 0, 0);
;             AT_EXP(s0, 8, p1);
;             __builtin_amdgcn_sched_barrier(0);
; #pragma unroll
;             for (int db = 0; db < NDB; ++db) o[db] = __builtin_amdgcn_mfma_f32_32x32x16_bf16(va[NDB + db], p1.b, o[db], 0, 0, 0);
;             AT_EXP(s1, 0, p2);
;             __builtin_amdgcn_sched_barrier(0);
; #pragma unroll
;             for (int db = 0; db < NDB; ++db) o[db] = __builtin_amdgcn_mfma_f32_32x32x16_bf16(vc[db], p2.b, o[db], 0, 0, 0);
;             AT_EXP(s1, 8, p3);
;             __builtin_amdgcn_sched_barrier(0);
; #pragma unroll
;             for (int db = 0; db < NDB; ++db) o[db] = __builtin_amdgcn_mfma_f32_32x32x16_bf16(vc[NDB + db], p3.b, o[db], 0, 0, 0);
;             __builtin_amdgcn_sched_barrier(0);
;     ...
;             l_run += ls0 + ls1;
	s_add_i32 s98, s80, 0x8000
	s_and_b32 s98, s98, 0x18000
	v_add3_u32 v203, s98, v178, v162
	ds_read_b128 v[204:207], v203
	ds_read_b128 v[208:211], v203 offset:4096
	v_add3_u32 v203, s98, v180, v162
	ds_read_b128 v[212:215], v203
	ds_read_b128 v[216:219], v203 offset:4096
	v_add3_u32 v203, s98, v182, v162
	ds_read_b128 v[220:223], v203
	ds_read_b128 v[224:227], v203 offset:4096
	v_add3_u32 v203, s98, v184, v162
	ds_read_b128 v[234:237], v203
	v_mfma_f32_32x32x16_bf16 v[50:65], v[146:149], v[246:249], v[50:65]
	v_exp_f32_e32 v82, v82
	v_exp_f32_e32 v83, v83
	v_add_f32_e32 v228, v228, v112
	v_add_f32_e32 v229, v229, v113
	v_cvt_pk_bf16_f32 v242, v106, v107
	v_mfma_f32_32x32x16_bf16 v[34:49], v[150:153], v[246:249], v[34:49]
	v_exp_f32_e32 v84, v84
	v_exp_f32_e32 v85, v85
	v_add_f32_e32 v228, v228, v82
	v_add_f32_e32 v229, v229, v83
	v_cvt_pk_bf16_f32 v243, v108, v109
	v_mfma_f32_32x32x16_bf16 v[18:33], v[154:157], v[246:249], v[18:33]
	v_exp_f32_e32 v86, v86
	v_exp_f32_e32 v87, v87
	v_add_f32_e32 v228, v228, v84
	v_add_f32_e32 v229, v229, v85
	v_cvt_pk_bf16_f32 v244, v110, v111
	v_mfma_f32_32x32x16_bf16 v[2:17], v[158:161], v[246:249], v[2:17]
	v_exp_f32_e32 v88, v88
	v_exp_f32_e32 v89, v89
	v_add_f32_e32 v228, v228, v86
	v_add_f32_e32 v229, v229, v87
	v_cvt_pk_bf16_f32 v245, v112, v113
	s_waitcnt lgkmcnt(7)
	v_mfma_f32_32x32x16_bf16 v[50:65], v[130:133], v[250:253], v[50:65]
	v_exp_f32_e32 v90, v90
	v_exp_f32_e32 v91, v91
	v_add_f32_e32 v228, v228, v88
	v_add_f32_e32 v229, v229, v89
	v_cvt_pk_bf16_f32 v246, v82, v83
	v_mfma_f32_32x32x16_bf16 v[34:49], v[134:137], v[250:253], v[34:49]
	v_exp_f32_e32 v92, v92
	v_exp_f32_e32 v93, v93
	v_add_f32_e32 v228, v228, v90
	v_add_f32_e32 v229, v229, v91
	v_cvt_pk_bf16_f32 v247, v84, v85
	v_mfma_f32_32x32x16_bf16 v[18:33], v[138:141], v[250:253], v[18:33]
	v_exp_f32_e32 v94, v94
	v_exp_f32_e32 v95, v95
	v_add_f32_e32 v228, v228, v92
	v_add_f32_e32 v229, v229, v93
	v_cvt_pk_bf16_f32 v248, v86, v87
	v_mfma_f32_32x32x16_bf16 v[2:17], v[142:145], v[250:253], v[2:17]
	v_exp_f32_e32 v96, v96
	v_exp_f32_e32 v97, v97
	v_add_f32_e32 v228, v228, v94
	v_add_f32_e32 v229, v229, v95
	v_cvt_pk_bf16_f32 v249, v88, v89
	v_add_f32_e32 v228, v228, v96
	v_add_f32_e32 v229, v229, v97
	v_cvt_pk_bf16_f32 v250, v90, v91
	v_cvt_pk_bf16_f32 v251, v92, v93
	v_cvt_pk_bf16_f32 v252, v94, v95
	v_cvt_pk_bf16_f32 v253, v96, v97
	v_add_f32_e32 v228, v228, v229
	v_cmp_nge_f32_e32 vcc, 0x53800000, v228
	s_cbranch_vccnz .LSPs_redo
	s_add_i32 s79, s79, 1
	s_add_i32 s78, s78, 0x8000
	s_addk_i32 s77, 0x100
	s_add_i32 s76, s76, 64
	v_add_f32_e32 v0, v0, v228
	v_lshl_add_u64 v[172:173], v[172:173], 0, s[48:49]
	s_cmpk_eq_i32 s77, 0x2000
	v_lshl_add_u64 v[174:175], v[174:175], 0, s[60:61]
	s_cbranch_scc0 .LSPs_top
	s_branch .LSPs_exit
.LSPs_pure:
	s_waitcnt lgkmcnt(0)
	s_add_i32 s98, s80, 0x8000
	s_and_b32 s98, s98, 0x18000
	v_add3_u32 v203, s98, v178, v162
	ds_read_b128 v[204:207], v203
	ds_read_b128 v[208:211], v203 offset:4096
	v_add3_u32 v203, s98, v180, v162
	ds_read_b128 v[212:215], v203
	ds_read_b128 v[216:219], v203 offset:4096
	v_add3_u32 v203, s98, v182, v162
	ds_read_b128 v[220:223], v203
	ds_read_b128 v[224:227], v203 offset:4096
	v_add3_u32 v203, s98, v184, v162
	ds_read_b128 v[234:237], v203
	v_exp_f32_e32 v98, v98
	v_exp_f32_e32 v99, v99
	v_exp_f32_e32 v100, v100
	v_exp_f32_e32 v101, v101
	v_exp_f32_e32 v102, v102
	v_exp_f32_e32 v103, v103
	v_exp_f32_e32 v104, v104
	v_exp_f32_e32 v105, v105
	v_cvt_pk_bf16_f32 v238, v98, v99
	v_cvt_pk_bf16_f32 v239, v100, v101
	v_cvt_pk_bf16_f32 v240, v102, v103
	v_cvt_pk_bf16_f32 v241, v104, v105
	v_mov_b32_e32 v228, v98
	v_mov_b32_e32 v229, v102
	v_add_f32_e32 v228, v228, v99
	v_add_f32_e32 v229, v229, v103
	v_add_f32_e32 v228, v228, v100
	v_add_f32_e32 v229, v229, v104
	v_add_f32_e32 v228, v228, v101
	v_add_f32_e32 v229, v229, v105
	v_exp_f32_e32 v106, v106
	v_exp_f32_e32 v107, v107
	v_exp_f32_e32 v108, v108
	v_exp_f32_e32 v109, v109
	v_exp_f32_e32 v110, v110
	v_exp_f32_e32 v111, v111
	v_exp_f32_e32 v112, v112
	v_exp_f32_e32 v113, v113
	v_cvt_pk_bf16_f32 v242, v106, v107
	v_cvt_pk_bf16_f32 v243, v108, v109
	v_cvt_pk_bf16_f32 v244, v110, v111
	v_cvt_pk_bf16_f32 v245, v112, v113
	v_add_f32_e32 v228, v228, v106
	v_add_f32_e32 v229, v229, v110
	v_add_f32_e32 v228, v228, v107
	v_add_f32_e32 v229, v229, v111
	v_add_f32_e32 v228, v228, v108
	v_add_f32_e32 v229, v229, v112
	v_add_f32_e32 v228, v228, v109
	v_add_f32_e32 v229, v229, v113
	v_exp_f32_e32 v82, v82
	v_exp_f32_e32 v83, v83
	v_exp_f32_e32 v84, v84
	v_exp_f32_e32 v85, v85
	v_exp_f32_e32 v86, v86
	v_exp_f32_e32 v87, v87
	v_exp_f32_e32 v88, v88
	v_exp_f32_e32 v89, v89
	v_cvt_pk_bf16_f32 v246, v82, v83
	v_cvt_pk_bf16_f32 v247, v84, v85
	v_cvt_pk_bf16_f32 v248, v86, v87
	v_cvt_pk_bf16_f32 v249, v88, v89
	v_add_f32_e32 v228, v228, v82
	v_add_f32_e32 v229, v229, v86
	v_add_f32_e32 v228, v228, v83
	v_add_f32_e32 v229, v229, v87
	v_add_f32_e32 v228, v228, v84
	v_add_f32_e32 v229, v229, v88
	v_add_f32_e32 v228, v228, v85
	v_add_f32_e32 v229, v229, v89
	v_exp_f32_e32 v90, v90
	v_exp_f32_e32 v91, v91
	v_exp_f32_e32 v92, v92
	v_exp_f32_e32 v93, v93
	v_exp_f32_e32 v94, v94
	v_exp_f32_e32 v95, v95
	v_exp_f32_e32 v96, v96
	v_exp_f32_e32 v97, v97
	v_cvt_pk_bf16_f32 v250, v90, v91
	v_cvt_pk_bf16_f32 v251, v92, v93
	v_cvt_pk_bf16_f32 v252, v94, v95
	v_cvt_pk_bf16_f32 v253, v96, v97
	v_add_f32_e32 v228, v228, v90
	v_add_f32_e32 v229, v229, v94
	v_add_f32_e32 v228, v228, v91
	v_add_f32_e32 v229, v229, v95
	v_add_f32_e32 v228, v228, v92
	v_add_f32_e32 v229, v229, v96
	v_add_f32_e32 v228, v228, v93
	v_add_f32_e32 v229, v229, v97
	v_add_f32_e32 v228, v228, v229
	v_cmp_nge_f32_e32 vcc, 0x53800000, v228
	s_cbranch_vccnz .LSPs_redo
	s_add_i32 s79, s79, 1
	s_add_i32 s78, s78, 0x8000
	s_addk_i32 s77, 0x100
	s_add_i32 s76, s76, 64
	v_add_f32_e32 v0, v0, v228
	v_lshl_add_u64 v[172:173], v[172:173], 0, s[48:49]
	s_cmpk_eq_i32 s77, 0x2000
	v_lshl_add_u64 v[174:175], v[174:175], 0, s[60:61]
	s_cbranch_scc0 .LSPs_top
	s_branch .LSPs_exit
; #define ALAS __attribute__((address_space(3)))
; template <bool WIN> ...
;     ...
;             f32x16 s0, s1;
;             const ALAS unsigned char* sb = lds + (tr & (NSTG - 1)) * STAGE;
;             {
;                 bf16x8 ka[8];
; #pragma unroll
;                 for (int ds = 0; ds < 4; ++ds) { ka[2 * ds] = *(const ALAS bf16x8*)(sb + kx[ds]); ka[2 * ds + 1] = *(const ALAS bf16x8*)(sb + kx[ds] + 4096); }
;                 __builtin_amdgcn_sched_barrier(0);
;                 s0 = __builtin_amdgcn_mfma_f32_32x32x16_bf16(ka[0], qf(0), cvec, 0, 0, 0);
;                 s1 = __builtin_amdgcn_mfma_f32_32x32x16_bf16(ka[1], qf(0), cvec, 0, 0, 0);
; #pragma unroll
;                 for (int ds = 1; ds < 4; ++ds) {
;                     s0 = __builtin_amdgcn_mfma_f32_32x32x16_bf16(ka[2 * ds], qf(ds), s0, 0, 0, 0);
;                     s1 = __builtin_amdgcn_mfma_f32_32x32x16_bf16(ka[2 * ds + 1], qf(ds), s1, 0, 0, 0);
;                 }
;             }
;             bf16x8 va[2 * NDB], vc[2 * NDB];
; #pragma unroll
;             for (int kk = 0; kk < 2; ++kk)
; #pragma unroll
;                 for (int db = 0; db < NDB; ++db) va[kk * NDB + db] = *(const ALAS bf16x8*)(sb + vx[kk] + db * 4096);
;             __builtin_amdgcn_sched_barrier(0);
;             if (near) {
;                 const ALAS float* lb = lut + (k0 + 8 * hi - qabs + LUTC);
; #pragma unroll
;                 for (int r = 0; r < 16; ++r) { s0[r] += lb[16 * (r >> 3) + (r & 7)]; s1[r] += lb[32 + 16 * (r >> 3) + (r & 7)];
;                     if ((r & 7) == 7) __builtin_amdgcn_sched_barrier(0); }
;             }
.LSPs_redo:
	v_add3_u32 v203, s80, v178, v162
	ds_read_b128 v[204:207], v203
	ds_read_b128 v[208:211], v203 offset:4096
	v_add3_u32 v203, s80, v180, v162
	ds_read_b128 v[212:215], v203
	ds_read_b128 v[216:219], v203 offset:4096
	v_add3_u32 v203, s80, v182, v162
	ds_read_b128 v[220:223], v203
	ds_read_b128 v[224:227], v203 offset:4096
	v_add3_u32 v203, s80, v184, v162
	ds_read_b128 v[234:237], v203
	ds_read_b128 v[130:133], v203 offset:4096
	s_waitcnt lgkmcnt(0)
	v_mfma_f32_32x32x16_bf16 v[98:113], v[204:207], v[126:129], v[66:81]
	v_mfma_f32_32x32x16_bf16 v[82:97], v[208:211], v[126:129], v[66:81]
	v_mfma_f32_32x32x16_bf16 v[98:113], v[212:215], v[122:125], v[98:113]
	v_mfma_f32_32x32x16_bf16 v[82:97], v[216:219], v[122:125], v[82:97]
	v_mfma_f32_32x32x16_bf16 v[98:113], v[220:223], v[118:121], v[98:113]
	v_mfma_f32_32x32x16_bf16 v[82:97], v[224:227], v[118:121], v[82:97]
	v_mfma_f32_32x32x16_bf16 v[98:113], v[234:237], v[114:117], v[98:113]
	v_mfma_f32_32x32x16_bf16 v[82:97], v[130:133], v[114:117], v[82:97]
	s_nop 7
	s_nop 7
	s_andn2_b64 vcc, exec, s[64:65]
	s_cbranch_vccnz .LSPs_redomax
	v_add_u32_e32 v203, s77, v171
	v_add_u32_e32 v204, 0x23b80, v203
	v_add_u32_e32 v206, 0x23c00, v203
	v_add_u32_e32 v210, 0x23c08, v203
	v_add_u32_e32 v208, 0x23b88, v203
	v_add_u32_e32 v218, 0x23c10, v203
	v_add_u32_e32 v212, 0x23b90, v203
	v_add_u32_e32 v216, 0x23c18, v203
	v_add_u32_e32 v214, 0x23b98, v203
	ds_read2_b32 v[204:205], v204 offset1:1
	ds_read2_b32 v[206:207], v206 offset1:1
	ds_read2_b32 v[208:209], v208 offset1:1
	ds_read2_b32 v[210:211], v210 offset1:1
	ds_read2_b32 v[212:213], v212 offset1:1
	ds_read2_b32 v[214:215], v214 offset1:1
	ds_read2_b32 v[216:217], v216 offset1:1
	ds_read2_b32 v[218:219], v218 offset1:1
	v_add_u32_e32 v220, 0x23bc0, v203
	v_add_u32_e32 v222, 0x23c40, v203
	v_add_u32_e32 v226, 0x23c48, v203
	v_add_u32_e32 v224, 0x23bc8, v203
	v_add_u32_e32 v228, 0x23bd0, v203
	v_add_u32_e32 v234, 0x23c58, v203
	ds_read2_b32 v[220:221], v220 offset1:1
	ds_read2_b32 v[222:223], v222 offset1:1
	ds_read2_b32 v[224:225], v224 offset1:1
	ds_read2_b32 v[226:227], v226 offset1:1
	v_add_u32_e32 v231, 0x23c50, v203
	v_add_u32_e32 v203, 0x23bd8, v203
	ds_read2_b32 v[228:229], v228 offset1:1
	ds_read2_b32 v[232:233], v203 offset1:1
	ds_read2_b32 v[234:235], v234 offset1:1
	ds_read2_b32 v[236:237], v231 offset1:1
	s_waitcnt lgkmcnt(10)
	v_pk_add_f32 v[104:105], v[104:105], v[214:215]
	v_pk_add_f32 v[102:103], v[102:103], v[212:213]
	v_pk_add_f32 v[100:101], v[100:101], v[208:209]
	s_waitcnt lgkmcnt(2)
	v_pk_add_f32 v[112:113], v[112:113], v[232:233]
	v_pk_add_f32 v[110:111], v[110:111], v[228:229]
	v_pk_add_f32 v[108:109], v[108:109], v[224:225]
	v_pk_add_f32 v[106:107], v[106:107], v[220:221]
	v_pk_add_f32 v[98:99], v[98:99], v[204:205]
	v_pk_add_f32 v[88:89], v[88:89], v[216:217]
	v_pk_add_f32 v[86:87], v[86:87], v[218:219]
	v_pk_add_f32 v[84:85], v[84:85], v[210:211]
	s_waitcnt lgkmcnt(1)
	v_pk_add_f32 v[96:97], v[96:97], v[234:235]
	s_waitcnt lgkmcnt(0)
	v_pk_add_f32 v[94:95], v[94:95], v[236:237]
	v_pk_add_f32 v[92:93], v[92:93], v[226:227]
	v_pk_add_f32 v[90:91], v[90:91], v[222:223]
	v_pk_add_f32 v[82:83], v[82:83], v[206:207]

; #define ALAS __attribute__((address_space(3)))
; template <bool WIN> ...
;     ...
;             union PFU { u32x4 u; bf16x8 b; };
;             PFU p0, p1, p2, p3;
;             AT_EXP(s0, 0, p0);
; #pragma unroll
;             for (int kk = 0; kk < 2; ++kk)
; #pragma unroll
;                 for (int db = 0; db < NDB; ++db) vc[kk * NDB + db] = *(const ALAS bf16x8*)(sb + vx[kk + 2] + db * 4096);
;             __builtin_amdgcn_sched_barrier(0);
; #pragma unroll
;             for (int db = 0; db < NDB; ++db) o[db] = __builtin_amdgcn_mfma_f32_32x32x16_bf16(va[db], p0.b, o[db], 0, 0, 0);
;             AT_EXP(s0, 8, p1);
;             __builtin_amdgcn_sched_barrier(0);
; #pragma unroll
;             for (int db = 0; db < NDB; ++db) o[db] = __builtin_amdgcn_mfma_f32_32x32x16_bf16(va[NDB + db], p1.b, o[db], 0, 0, 0);
;             AT_EXP(s1, 0, p2);
;             __builtin_amdgcn_sched_barrier(0);
; #pragma unroll
;             for (int db = 0; db < NDB; ++db) o[db] = __builtin_amdgcn_mfma_f32_32x32x16_bf16(vc[db], p2.b, o[db], 0, 0, 0);
;             AT_EXP(s1, 8, p3);
;             __builtin_amdgcn_sched_barrier(0);
; #pragma unroll
;             for (int db = 0; db < NDB; ++db) o[db] = __builtin_amdgcn_mfma_f32_32x32x16_bf16(vc[NDB + db], p3.b, o[db], 0, 0, 0);
;             __builtin_amdgcn_sched_barrier(0);
;     ...
;             l_run += ls0 + ls1;
.LSPs_pure2:
	s_waitcnt lgkmcnt(0)
	s_add_i32 s98, s80, 0x8000
	s_and_b32 s98, s98, 0x18000
	v_add3_u32 v203, s98, v178, v162
	ds_read_b128 v[204:207], v203
	ds_read_b128 v[208:211], v203 offset:4096
	v_add3_u32 v203, s98, v180, v162
	ds_read_b128 v[212:215], v203
	ds_read_b128 v[216:219], v203 offset:4096
	v_add3_u32 v203, s98, v182, v162
	ds_read_b128 v[220:223], v203
	ds_read_b128 v[224:227], v203 offset:4096
	v_add3_u32 v203, s98, v184, v162
	ds_read_b128 v[234:237], v203
	v_exp_f32_e32 v98, v98
	v_exp_f32_e32 v99, v99
	v_exp_f32_e32 v100, v100
	v_exp_f32_e32 v101, v101
	v_exp_f32_e32 v102, v102
	v_exp_f32_e32 v103, v103
	v_exp_f32_e32 v104, v104
	v_exp_f32_e32 v105, v105
	v_cvt_pk_bf16_f32 v238, v98, v99
	v_cvt_pk_bf16_f32 v239, v100, v101
	v_cvt_pk_bf16_f32 v240, v102, v103
	v_cvt_pk_bf16_f32 v241, v104, v105
	v_mov_b32_e32 v228, v98
	v_mov_b32_e32 v229, v102
	v_add_f32_e32 v228, v228, v99
	v_add_f32_e32 v229, v229, v103
	v_add_f32_e32 v228, v228, v100
	v_add_f32_e32 v229, v229, v104
	v_add_f32_e32 v228, v228, v101
	v_add_f32_e32 v229, v229, v105
	v_exp_f32_e32 v106, v106
	v_exp_f32_e32 v107, v107
	v_exp_f32_e32 v108, v108
	v_exp_f32_e32 v109, v109
	v_exp_f32_e32 v110, v110
	v_exp_f32_e32 v111, v111
	v_exp_f32_e32 v112, v112
	v_exp_f32_e32 v113, v113
	v_cvt_pk_bf16_f32 v242, v106, v107
	v_cvt_pk_bf16_f32 v243, v108, v109
	v_cvt_pk_bf16_f32 v244, v110, v111
	v_cvt_pk_bf16_f32 v245, v112, v113
	v_add_f32_e32 v228, v228, v106
	v_add_f32_e32 v229, v229, v110
	v_add_f32_e32 v228, v228, v107
	v_add_f32_e32 v229, v229, v111
	v_add_f32_e32 v228, v228, v108
	v_add_f32_e32 v229, v229, v112
	v_add_f32_e32 v228, v228, v109
	v_add_f32_e32 v229, v229, v113
	v_exp_f32_e32 v82, v82
	v_exp_f32_e32 v83, v83
	v_exp_f32_e32 v84, v84
	v_exp_f32_e32 v85, v85
	v_exp_f32_e32 v86, v86
	v_exp_f32_e32 v87, v87
	v_exp_f32_e32 v88, v88
	v_exp_f32_e32 v89, v89
	v_cvt_pk_bf16_f32 v246, v82, v83
	v_cvt_pk_bf16_f32 v247, v84, v85
	v_cvt_pk_bf16_f32 v248, v86, v87
	v_cvt_pk_bf16_f32 v249, v88, v89
	v_add_f32_e32 v228, v228, v82
	v_add_f32_e32 v229, v229, v86
	v_add_f32_e32 v228, v228, v83
	v_add_f32_e32 v229, v229, v87
	v_add_f32_e32 v228, v228, v84
	v_add_f32_e32 v229, v229, v88
	v_add_f32_e32 v228, v228, v85
	v_add_f32_e32 v229, v229, v89
	v_exp_f32_e32 v90, v90
	v_exp_f32_e32 v91, v91
	v_exp_f32_e32 v92, v92
	v_exp_f32_e32 v93, v93
	v_exp_f32_e32 v94, v94
	v_exp_f32_e32 v95, v95
	v_exp_f32_e32 v96, v96
	v_exp_f32_e32 v97, v97
	v_cvt_pk_bf16_f32 v250, v90, v91
	v_cvt_pk_bf16_f32 v251, v92, v93
	v_cvt_pk_bf16_f32 v252, v94, v95
	v_cvt_pk_bf16_f32 v253, v96, v97
	v_add_f32_e32 v228, v228, v90
	v_add_f32_e32 v229, v229, v94
	v_add_f32_e32 v228, v228, v91
	v_add_f32_e32 v229, v229, v95
	v_add_f32_e32 v228, v228, v92
	v_add_f32_e32 v229, v229, v96
	v_add_f32_e32 v228, v228, v93
	v_add_f32_e32 v229, v229, v97
	v_add_f32_e32 v228, v228, v229
	s_add_i32 s79, s79, 1
	s_add_i32 s78, s78, 0x8000
	s_addk_i32 s77, 0x100
	s_add_i32 s76, s76, 64
	v_add_f32_e32 v0, v0, v228
	v_lshl_add_u64 v[172:173], v[172:173], 0, s[48:49]
	s_cmpk_eq_i32 s77, 0x2000
	v_lshl_add_u64 v[174:175], v[174:175], 0, s[60:61]
	s_cbranch_scc0 .LSPs_top
	s_branch .LSPs_exit
.LSPs_exit:
	s_add_i32 s99, s78, 0xfffe8000
	s_and_b32 s99, s99, 0x18000
	v_add3_u32 v203, s99, v179, v187
	ds_read_b128 v[146:149], v203 offset:16384
	ds_read_b128 v[150:153], v203 offset:20480
	ds_read_b128 v[154:157], v203 offset:24576
	ds_read_b128 v[158:161], v203 offset:28672
	v_add3_u32 v203, s99, v181, v187
	ds_read_b128 v[130:133], v203 offset:16384
	ds_read_b128 v[134:137], v203 offset:20480
	ds_read_b128 v[138:141], v203 offset:24576
	ds_read_b128 v[142:145], v203 offset:28672
	s_waitcnt lgkmcnt(4)
	v_mfma_f32_32x32x16_bf16 v[50:65], v[146:149], v[238:241], v[50:65]
	v_mfma_f32_32x32x16_bf16 v[34:49], v[150:153], v[238:241], v[34:49]
	v_mfma_f32_32x32x16_bf16 v[18:33], v[154:157], v[238:241], v[18:33]
	v_mfma_f32_32x32x16_bf16 v[2:17], v[158:161], v[238:241], v[2:17]
	v_add3_u32 v203, s99, v183, v187
	ds_read_b128 v[146:149], v203 offset:16384
	ds_read_b128 v[150:153], v203 offset:20480
	ds_read_b128 v[154:157], v203 offset:24576
	ds_read_b128 v[158:161], v203 offset:28672
	s_waitcnt lgkmcnt(4)
	v_mfma_f32_32x32x16_bf16 v[50:65], v[130:133], v[242:245], v[50:65]
	v_mfma_f32_32x32x16_bf16 v[34:49], v[134:137], v[242:245], v[34:49]
	v_mfma_f32_32x32x16_bf16 v[18:33], v[138:141], v[242:245], v[18:33]
	v_mfma_f32_32x32x16_bf16 v[2:17], v[142:145], v[242:245], v[2:17]
	v_add3_u32 v203, s99, v190, v187
	ds_read_b128 v[130:133], v203 offset:16384
	ds_read_b128 v[134:137], v203 offset:20480
	ds_read_b128 v[138:141], v203 offset:24576
	ds_read_b128 v[142:145], v203 offset:28672
	s_waitcnt lgkmcnt(4)
	v_mfma_f32_32x32x16_bf16 v[50:65], v[146:149], v[246:249], v[50:65]
	v_mfma_f32_32x32x16_bf16 v[34:49], v[150:153], v[246:249], v[34:49]
	v_mfma_f32_32x32x16_bf16 v[18:33], v[154:157], v[246:249], v[18:33]
	v_mfma_f32_32x32x16_bf16 v[2:17], v[158:161], v[246:249], v[2:17]
	s_waitcnt lgkmcnt(0)
	v_mfma_f32_32x32x16_bf16 v[50:65], v[130:133], v[250:253], v[50:65]
	v_mfma_f32_32x32x16_bf16 v[34:49], v[134:137], v[250:253], v[34:49]
	v_mfma_f32_32x32x16_bf16 v[18:33], v[138:141], v[250:253], v[18:33]
	v_mfma_f32_32x32x16_bf16 v[2:17], v[142:145], v[250:253], v[2:17]
	s_branch .LBB0_286
